# DeltaNet state wave: first two packed-state operand fragments of a step are formed at the end of the previous step (in the shadow of the O read-back), off the step-start critical path
# speedup vs baseline: 1.0488x; 1.0006x over previous
; __device__ __forceinline__ int opaque_tid() { int t = threadIdx.x; asm volatile("" : "+v"(t)); return t; }
; #define LAS __attribute__((address_space(3)))
; #define BAR_LDS() do { asm volatile("s_waitcnt lgkmcnt(0)" ::: "memory"); __builtin_amdgcn_s_barrier(); asm volatile("" ::: "memory"); } while (0)
; #define MFMA32(a, b, c) __builtin_amdgcn_mfma_f32_32x32x16_bf16((a), (b), (c), 0, 0, 0)
; template <int VAR> __device__ __forceinline__ void dn_scan3(LAS unsigned char* lds, const bf16_t* P, const float* AB, const bf16_t* TP, bf16_t* OB) {
;     ...
;             f32x16 S[4];
; #pragma unroll
;             for (int kt = 0; kt < 4; ++kt)
; #pragma unroll
;                 for (int x = 0; x < 16; ++x) S[kt][x] = 0.f;
;             BAR_LDS();
;             for (int step = 0; step < 260; ++step) {
;                 const int lane = opaque_tid() & 63, r = lane & 31, h = lane >> 5;
;                 LAS unsigned char* base = lds + (step & 1) * DN_DIR;
;                 LAS bf16_t* Kb = (LAS bf16_t*)(base + DN_KB); LAS bf16_t* Qb = (LAS bf16_t*)(base + DN_QB); LAS bf16_t* Vb = (LAS bf16_t*)(base + DN_VB);
;                 LAS bf16_t* Tb = (LAS bf16_t*)(base + DN_TB); LAS bf16_t* Ab = (LAS bf16_t*)(base + DN_AB);
;                 LAS float* sc_beta = (LAS float*)(base + DN_SC); LAS float* sc_eg = sc_beta + 128; LAS float* sc_tail = sc_beta + 192; LAS float* sc_dl = sc_beta + 256;
;                 int rb; bool f_; dn_step_rb(step, dir, b, rb, f_);
;                 if (VAR != 2) {
;                 f32x16 KS[2], QS[2];
; #pragma unroll
;                 for (int mt = 0; mt < 2; ++mt)
; #pragma unroll
;                     for (int x = 0; x < 16; ++x) { KS[mt][x] = 0.f; QS[mt][x] = 0.f; }
; #pragma unroll
;                 for (int ks = 0; ks < 8; ++ks) {
;                     const bf16x8 sp = pack_step(S[ks >> 1], ks & 1);
; #pragma unroll
;                     for (int mt = 0; mt < 2; ++mt) { KS[mt] = MFMA32(frag_perm(Kb, 136, 32 * mt + r, ks, h), sp, KS[mt]); QS[mt] = MFMA32(frag_perm(Qb, 136, 32 * mt + r, ks, h), sp, QS[mt]); }
.Ldn_full:
	s_setprio 3
	v_mov_b32_e32 v2, 0
	s_mov_b32 s40, 0
	v_mov_b32_e32 v3, v2
	v_mov_b32_e32 v4, v2
	v_mov_b32_e32 v5, v2
	v_mov_b32_e32 v6, v2
	v_mov_b32_e32 v7, v2
	v_mov_b32_e32 v8, v2
	v_mov_b32_e32 v9, v2
	v_mov_b32_e32 v10, v2
	v_mov_b32_e32 v11, v2
	v_mov_b32_e32 v12, v2
	v_mov_b32_e32 v13, v2
	v_mov_b32_e32 v14, v2
	v_mov_b32_e32 v15, v2
	v_mov_b32_e32 v16, v2
	v_mov_b32_e32 v17, v2
	v_mov_b32_e32 v18, v2
	v_mov_b32_e32 v19, v2
	v_mov_b32_e32 v20, v2
	v_mov_b32_e32 v21, v2
	v_mov_b32_e32 v22, v2
	v_mov_b32_e32 v23, v2
	v_mov_b32_e32 v24, v2
	v_mov_b32_e32 v25, v2
	v_mov_b32_e32 v26, v2
	v_mov_b32_e32 v27, v2
	v_mov_b32_e32 v28, v2
	v_mov_b32_e32 v29, v2
	v_mov_b32_e32 v30, v2
	v_mov_b32_e32 v31, v2
	v_mov_b32_e32 v32, v2
	v_mov_b32_e32 v33, v2
	v_mov_b32_e32 v34, v2
	v_mov_b32_e32 v35, v2
	v_mov_b32_e32 v36, v2
	v_mov_b32_e32 v37, v2
	v_mov_b32_e32 v38, v2
	v_mov_b32_e32 v39, v2
	v_mov_b32_e32 v40, v2
	v_mov_b32_e32 v41, v2
	v_mov_b32_e32 v42, v2
	v_mov_b32_e32 v43, v2
	v_mov_b32_e32 v44, v2
	v_mov_b32_e32 v45, v2
	v_mov_b32_e32 v46, v2
	v_mov_b32_e32 v47, v2
	v_mov_b32_e32 v48, v2
	v_mov_b32_e32 v49, v2
	v_mov_b32_e32 v50, v2
	v_mov_b32_e32 v51, v2
	v_mov_b32_e32 v52, v2
	v_mov_b32_e32 v53, v2
	v_mov_b32_e32 v54, v2
	v_mov_b32_e32 v55, v2
	v_mov_b32_e32 v56, v2
	v_mov_b32_e32 v57, v2
	v_mov_b32_e32 v58, v2
	v_mov_b32_e32 v59, v2
	v_mov_b32_e32 v60, v2
	v_mov_b32_e32 v61, v2
	v_mov_b32_e32 v62, v2
	v_mov_b32_e32 v63, v2
	v_mov_b32_e32 v64, v2
	v_mov_b32_e32 v65, v2
	v_and_b32_e32 v212, 31, v188
	v_bfe_u32 v213, v188, 5, 1
	v_mul_u32_u24_e32 v214, 0x110, v212
	v_lshl_add_u32 v207, v213, 4, v214
	v_mul_u32_u24_e32 v214, 0x90, v212
	v_lshl_add_u32 v210, v213, 4, v214
	v_lshlrev_b32_e32 v214, 1, v212
	v_lshl_add_u32 v214, v213, 10, v214
	v_add_u32_e32 v208, s18, v214
	v_lshlrev_b32_e32 v214, 4, v213
	v_add_u32_e32 v209, 0x11000, v214
	v_bfe_u32 v214, v188, 2, 2
	v_and_b32_e32 v215, 3, v188
	v_lshlrev_b32_e32 v215, 3, v215
	v_bfe_u32 v216, v188, 4, 1
	v_lshl_add_u32 v215, v216, 5, v215
	v_lshlrev_b32_e32 v216, 3, v214
	v_lshl_add_u32 v216, v213, 2, v216
	v_and_b32_e32 v217, 3, v214
	v_add_u32_e32 v217, v217, v216
	v_mul_u32_u24_e32 v217, 0x110, v217
	v_add_u32_e32 v211, v217, v215
	v_add_u32_e32 v217, 1, v214
	v_and_b32_e32 v217, 3, v217
	v_add_u32_e32 v217, v217, v216
	v_mul_u32_u24_e32 v217, 0x110, v217
	v_add_u32_e32 v201, v217, v215
	v_add_u32_e32 v217, 2, v214
	v_and_b32_e32 v217, 3, v217
	v_add_u32_e32 v217, v217, v216
	v_mul_u32_u24_e32 v217, 0x110, v217
	v_add_u32_e32 v180, v217, v215
	v_add_u32_e32 v217, 3, v214
	v_and_b32_e32 v217, 3, v217
	v_add_u32_e32 v217, v217, v216
	v_mul_u32_u24_e32 v217, 0x110, v217
	v_add_u32_e32 v217, v217, v215
	v_lshl_or_b32 v180, v217, 16, v180
	s_and_b32 s57, s54, 1
	s_lshr_b32 s45, s54, 5
	s_lshl_b32 s55, s45, 2
	s_addk_i32 s55, 0x200
	s_lshl_b32 s56, s45, 8
	s_bfe_u32 s48, s54, 0x40001
	s_lshl_b32 s48, s48, 8
	s_add_i32 s48, s48, s18
	s_add_u32 s58, s8, s48
	s_addc_u32 s59, s9, 0
	s_mul_i32 s49, s57, 63
	s_mov_b32 s60, 0
	s_lshl_b32 s61, s57, 15
	s_sub_i32 s61, 0x4000, s61
	s_lshl_b32 s62, s61, 1
	v_and_b32_e32 v212, 63, v188
	v_lshrrev_b32_e32 v213, 4, v212
	v_and_b32_e32 v214, 15, v212
	v_lshlrev_b32_e32 v214, 2, v214
	v_lshl_add_u32 v0, v213, 8, v214
	v_add_u32_e32 v0, s18, v0
	v_xor_b32_e32 v215, s49, v213
	v_lshl_add_u32 v194, v215, 12, v214
	v_mov_b32_e32 v218, 0
	v_mov_b32_e32 v219, 0
	v_mov_b32_e32 v220, 0
	v_mov_b32_e32 v221, 0
	v_mov_b32_e32 v222, 0
	v_mov_b32_e32 v223, 0
	v_mov_b32_e32 v224, 0
	v_mov_b32_e32 v225, 0
.LBB0_377:
	s_bitcmp1_b32 s40, 0
	s_cselect_b32 s41, 0x11600, 0
	v_add_u32_e32 v212, s41, v207
	v_add_u32_e32 v214, s41, v209
	v_add_u32_e32 v213, s41, v208
	v_add_u32_e32 v215, s41, v210
	s_add_i32 s42, s41, 0x11400
	v_mov_b32_e32 v217, s42
	v_add_u32_e32 v179, s41, v0
	s_add_i32 s44, s40, -4
	s_cmp_lt_u32 s40, 4
	s_cselect_b32 s44, s40, s44
	s_cselect_b32 s45, 3, 0xff
	s_cselect_b32 s48, s55, s56
	s_sub_i32 s45, s45, s44
	s_cmp_eq_u32 s57, 0
	s_cselect_b32 s44, s44, s45
	s_add_i32 s44, s44, s48
	s_lshl_b32 s44, s44, 18
	s_add_u32 s42, s58, s44
	s_addc_u32 s43, s59, 0
	ds_read_b128 v[138:141], v212 offset:0
	ds_read_b128 v[142:145], v212 offset:32
	ds_read_b128 v[146:149], v212 offset:64
	ds_read_b128 v[150:153], v212 offset:96
	ds_read_b128 v[154:157], v212 offset:128
	ds_read_b128 v[158:161], v212 offset:160
	ds_read_b128 v[162:165], v212 offset:192
	ds_read_b128 v[166:169], v212 offset:224
	s_waitcnt lgkmcnt(7)
	v_mfma_f32_32x32x16_bf16 v[66:81], v[138:141], v[218:221], 0
	v_cvt_pk_bf16_f32 v226, v34, v35
	v_cvt_pk_bf16_f32 v228, v38, v39
	v_cvt_pk_bf16_f32 v227, v36, v37
	v_cvt_pk_bf16_f32 v229, v40, v41
	v_permlane32_swap_b32_e32 v226, v228
	ds_read_b128 v[138:141], v212 offset:8704
	v_permlane32_swap_b32_e32 v227, v229
	ds_read_b128 v[170:173], v212 offset:8736
	s_waitcnt lgkmcnt(8)
	v_mfma_f32_32x32x16_bf16 v[66:81], v[142:145], v[222:225], v[66:81]
	v_cvt_pk_bf16_f32 v230, v42, v43
	v_cvt_pk_bf16_f32 v232, v46, v47
	v_cvt_pk_bf16_f32 v231, v44, v45
	v_cvt_pk_bf16_f32 v233, v48, v49
	v_permlane32_swap_b32_e32 v230, v232
	ds_read_b128 v[142:145], v212 offset:8768
	v_permlane32_swap_b32_e32 v231, v233
	s_waitcnt lgkmcnt(8)
	v_mfma_f32_32x32x16_bf16 v[66:81], v[146:149], v[226:229], v[66:81]
	v_cvt_pk_bf16_f32 v234, v18, v19
	v_cvt_pk_bf16_f32 v236, v22, v23
	v_cvt_pk_bf16_f32 v235, v20, v21
	v_cvt_pk_bf16_f32 v237, v24, v25
	v_permlane32_swap_b32_e32 v234, v236
	ds_read_b128 v[146:149], v212 offset:8800
	v_permlane32_swap_b32_e32 v235, v237
	s_waitcnt lgkmcnt(8)
; #define LAS __attribute__((address_space(3)))
; #define MFMA32(a, b, c) __builtin_amdgcn_mfma_f32_32x32x16_bf16((a), (b), (c), 0, 0, 0)
; template <int VAR> __device__ __forceinline__ void dn_scan3(LAS unsigned char* lds, const bf16_t* P, const float* AB, const bf16_t* TP, bf16_t* OB) {
;     ...
;                 for (int ks = 0; ks < 8; ++ks) {
;                     const bf16x8 sp = pack_step(S[ks >> 1], ks & 1);
; #pragma unroll
;                     for (int mt = 0; mt < 2; ++mt) { KS[mt] = MFMA32(frag_perm(Kb, 136, 32 * mt + r, ks, h), sp, KS[mt]); QS[mt] = MFMA32(frag_perm(Qb, 136, 32 * mt + r, ks, h), sp, QS[mt]); }
;                 }
;                 __builtin_amdgcn_iglp_opt(0);
; #pragma unroll
;                 for (int mt = 0; mt < 2; ++mt)
; #pragma unroll
;                     for (int g4 = 0; g4 < 4; ++g4) { const int i0 = 32 * mt + 8 * g4 + 4 * h;
;                         const f32x4 bv = *(const LAS f32x4*)(sc_beta + i0), ev = *(const LAS f32x4*)(sc_eg + i0);
; #pragma unroll
;                         for (int e = 0; e < 4; ++e) { const int x = 4 * g4 + e; KS[mt][x] = bv[e] * (bf2f(Vb[(i0 + e) * 128 + 32 * w + r]) - ev[e] * KS[mt][x]); } }
;                 bf16x8 Xp[4];
; #pragma unroll
;                 for (int ks = 0; ks < 4; ++ks) Xp[ks] = pack_step(KS[ks >> 1], ks & 1);
	v_mfma_f32_32x32x16_bf16 v[66:81], v[150:153], v[230:233], v[66:81]
	v_cvt_pk_bf16_f32 v238, v26, v27
	v_cvt_pk_bf16_f32 v240, v30, v31
	v_cvt_pk_bf16_f32 v239, v28, v29
	v_cvt_pk_bf16_f32 v241, v32, v33
	v_permlane32_swap_b32_e32 v238, v240
	ds_read_b128 v[150:153], v212 offset:8832
	v_permlane32_swap_b32_e32 v239, v241
	s_waitcnt lgkmcnt(8)
	v_mfma_f32_32x32x16_bf16 v[66:81], v[154:157], v[234:237], v[66:81]
	v_cvt_pk_bf16_f32 v242, v2, v3
	v_cvt_pk_bf16_f32 v244, v6, v7
	v_cvt_pk_bf16_f32 v243, v4, v5
	v_cvt_pk_bf16_f32 v245, v8, v9
	v_permlane32_swap_b32_e32 v242, v244
	ds_read_b128 v[154:157], v212 offset:8864
	v_permlane32_swap_b32_e32 v243, v245
	s_waitcnt lgkmcnt(8)
	v_mfma_f32_32x32x16_bf16 v[66:81], v[158:161], v[238:241], v[66:81]
	v_cvt_pk_bf16_f32 v246, v10, v11
	v_cvt_pk_bf16_f32 v248, v14, v15
	v_cvt_pk_bf16_f32 v247, v12, v13
	v_cvt_pk_bf16_f32 v249, v16, v17
	v_permlane32_swap_b32_e32 v246, v248
	ds_read_b128 v[158:161], v212 offset:8896
	v_permlane32_swap_b32_e32 v247, v249
	ds_read_u16 v114, v213 offset:34816
	ds_read_u16 v115, v213 offset:35072
	ds_read_u16 v116, v213 offset:35328
	ds_read_u16 v117, v213 offset:35584
	ds_read_b128 v[118:121], v214 offset:0
	ds_read_b128 v[122:125], v214 offset:512
	s_waitcnt lgkmcnt(14)
	v_mfma_f32_32x32x16_bf16 v[66:81], v[162:165], v[242:245], v[66:81]
	ds_read_u16 v126, v213 offset:36864
	ds_read_u16 v127, v213 offset:37120
	ds_read_u16 v128, v213 offset:37376
	ds_read_u16 v129, v213 offset:37632
	ds_read_b128 v[130:133], v214 offset:32
	ds_read_b128 v[134:137], v214 offset:544
	ds_read_b128 v[162:165], v212 offset:8928
	v_mfma_f32_32x32x16_bf16 v[66:81], v[166:169], v[246:249], v[66:81]
	ds_read_b128 v[166:169], v212 offset:17408
	v_mfma_f32_32x32x16_bf16 v[82:97], v[138:141], v[218:221], 0
	ds_read_b128 v[138:141], v212 offset:17440
	v_mfma_f32_32x32x16_bf16 v[82:97], v[170:173], v[222:225], v[82:97]
	ds_read_b128 v[170:173], v212 offset:17472
	v_mfma_f32_32x32x16_bf16 v[82:97], v[142:145], v[226:229], v[82:97]
	v_lshlrev_b32_e32 v114, 16, v114
	s_waitcnt lgkmcnt(14)
	v_lshlrev_b32_e32 v115, 16, v115
	s_waitcnt lgkmcnt(13)
	v_lshlrev_b32_e32 v116, 16, v116
	s_waitcnt lgkmcnt(12)
	v_lshlrev_b32_e32 v117, 16, v117
	s_waitcnt lgkmcnt(10)
	v_fma_f32 v114, -v66, v122, v114
	v_fma_f32 v115, -v67, v123, v115
	v_fma_f32 v116, -v68, v124, v116
	v_fma_f32 v117, -v69, v125, v117
	v_mul_f32_e32 v66, v118, v114
	v_mul_f32_e32 v67, v119, v115
	v_mul_f32_e32 v68, v120, v116
	v_mul_f32_e32 v69, v121, v117
	ds_read_u16 v114, v213 offset:38912
	ds_read_u16 v115, v213 offset:39168
	ds_read_u16 v116, v213 offset:39424
	ds_read_u16 v117, v213 offset:39680
	ds_read_b128 v[118:121], v214 offset:64
	ds_read_b128 v[122:125], v214 offset:576
	ds_read_b128 v[142:145], v212 offset:17504
	v_mfma_f32_32x32x16_bf16 v[82:97], v[146:149], v[230:233], v[82:97]
	v_lshlrev_b32_e32 v126, 16, v126
	v_lshlrev_b32_e32 v127, 16, v127
	s_waitcnt lgkmcnt(14)
	v_lshlrev_b32_e32 v128, 16, v128
	s_waitcnt lgkmcnt(13)
	v_lshlrev_b32_e32 v129, 16, v129
	s_waitcnt lgkmcnt(11)
	v_fma_f32 v126, -v70, v134, v126
	v_fma_f32 v127, -v71, v135, v127
	v_fma_f32 v128, -v72, v136, v128
	v_fma_f32 v129, -v73, v137, v129
	v_mul_f32_e32 v70, v130, v126
	v_mul_f32_e32 v71, v131, v127
	v_mul_f32_e32 v72, v132, v128
	v_mul_f32_e32 v73, v133, v129
	ds_read_u16 v126, v213 offset:40960
	ds_read_u16 v127, v213 offset:41216
	ds_read_u16 v128, v213 offset:41472
	ds_read_u16 v129, v213 offset:41728
	ds_read_b128 v[130:133], v214 offset:96
	ds_read_b128 v[134:137], v214 offset:608
	ds_read_b128 v[146:149], v212 offset:17536
	v_mfma_f32_32x32x16_bf16 v[82:97], v[150:153], v[234:237], v[82:97]
	v_cvt_pk_bf16_f32 v150, v66, v67
	v_cvt_pk_bf16_f32 v152, v70, v71
	v_cvt_pk_bf16_f32 v151, v68, v69
	v_cvt_pk_bf16_f32 v153, v72, v73
	v_permlane32_swap_b32_e32 v150, v152
	s_nop 0
	v_permlane32_swap_b32_e32 v151, v153
	s_waitcnt lgkmcnt(13)
	v_lshlrev_b32_e32 v114, 16, v114
	s_waitcnt lgkmcnt(12)
	v_lshlrev_b32_e32 v115, 16, v115
	s_waitcnt lgkmcnt(11)
	v_lshlrev_b32_e32 v116, 16, v116
	s_waitcnt lgkmcnt(10)
	v_lshlrev_b32_e32 v117, 16, v117
	s_waitcnt lgkmcnt(8)
	v_fma_f32 v114, -v74, v122, v114
	v_fma_f32 v115, -v75, v123, v115
	v_fma_f32 v116, -v76, v124, v116
	v_fma_f32 v117, -v77, v125, v117
	v_mul_f32_e32 v74, v118, v114
	v_mul_f32_e32 v75, v119, v115
	v_mul_f32_e32 v76, v120, v116
	v_mul_f32_e32 v77, v121, v117
	v_mfma_f32_32x32x16_bf16 v[82:97], v[154:157], v[238:241], v[82:97]
	s_waitcnt lgkmcnt(6)
	v_lshlrev_b32_e32 v126, 16, v126
	s_waitcnt lgkmcnt(5)
	v_lshlrev_b32_e32 v127, 16, v127
	s_waitcnt lgkmcnt(4)
	v_lshlrev_b32_e32 v128, 16, v128
	s_waitcnt lgkmcnt(3)
	v_lshlrev_b32_e32 v129, 16, v129
	s_waitcnt lgkmcnt(1)
	v_fma_f32 v126, -v78, v134, v126
	v_fma_f32 v127, -v79, v135, v127
	v_fma_f32 v128, -v80, v136, v128
	v_fma_f32 v129, -v81, v137, v129
	v_mul_f32_e32 v78, v130, v126
	v_mul_f32_e32 v79, v131, v127
	v_mul_f32_e32 v80, v132, v128
	v_mul_f32_e32 v81, v133, v129
	ds_read_u16 v114, v213 offset:43008
	ds_read_u16 v115, v213 offset:43264
	ds_read_u16 v116, v213 offset:43520
	ds_read_u16 v117, v213 offset:43776
	ds_read_b128 v[118:121], v214 offset:128
	ds_read_b128 v[122:125], v214 offset:640
	ds_read_b128 v[154:157], v212 offset:17568
	v_mfma_f32_32x32x16_bf16 v[82:97], v[158:161], v[242:245], v[82:97]
	v_cvt_pk_bf16_f32 v158, v74, v75
	v_cvt_pk_bf16_f32 v160, v78, v79
	v_cvt_pk_bf16_f32 v159, v76, v77
	v_cvt_pk_bf16_f32 v161, v80, v81
	v_permlane32_swap_b32_e32 v158, v160
	s_nop 0
	v_permlane32_swap_b32_e32 v159, v161
	ds_read_u16 v126, v213 offset:45056
	ds_read_u16 v127, v213 offset:45312
	ds_read_u16 v128, v213 offset:45568
	ds_read_u16 v129, v213 offset:45824
	ds_read_b128 v[130:133], v214 offset:160
	ds_read_b128 v[134:137], v214 offset:672
	v_mfma_f32_32x32x16_bf16 v[82:97], v[162:165], v[246:249], v[82:97]
	ds_read_b128 v[162:165], v212 offset:17600
	v_mfma_f32_32x32x16_bf16 v[98:113], v[166:169], v[218:221], 0
	ds_read_b128 v[166:169], v212 offset:17632
	v_mfma_f32_32x32x16_bf16 v[98:113], v[138:141], v[222:225], v[98:113]
	ds_read_b128 v[138:141], v212 offset:26112
	v_mfma_f32_32x32x16_bf16 v[98:113], v[170:173], v[226:229], v[98:113]
	v_lshlrev_b32_e32 v114, 16, v114
	s_waitcnt lgkmcnt(14)
; template <int VAR> __device__ __forceinline__ void dn_scan3(LAS unsigned char* lds, const bf16_t* P, const float* AB, const bf16_t* TP, bf16_t* OB) {
;     ...
;                 for (int mt = 0; mt < 2; ++mt)
; #pragma unroll
;                     for (int g4 = 0; g4 < 4; ++g4) { const int i0 = 32 * mt + 8 * g4 + 4 * h;
;                         const f32x4 bv = *(const LAS f32x4*)(sc_beta + i0), ev = *(const LAS f32x4*)(sc_eg + i0);
; #pragma unroll
;                         for (int e = 0; e < 4; ++e) { const int x = 4 * g4 + e; KS[mt][x] = bv[e] * (bf2f(Vb[(i0 + e) * 128 + 32 * w + r]) - ev[e] * KS[mt][x]); } }
;                 bf16x8 Xp[4];
; #pragma unroll
;                 for (int ks = 0; ks < 4; ++ks) Xp[ks] = pack_step(KS[ks >> 1], ks & 1);
;                 f32x16 VN[2];
; #pragma unroll
;                 for (int mt = 0; mt < 2; ++mt) {
; #pragma unroll
;                     for (int x = 0; x < 16; ++x) VN[mt][x] = 0.f;
; #pragma unroll
;                     for (int ks = 0; ks < 4; ++ks) if (ks < 2 * mt + 2) VN[mt] = MFMA32(frag_perm(Tb, 72, 32 * mt + r, ks, h), Xp[ks], VN[mt]);
;                 }
;                 bf16x8 VNp[4];
; #pragma unroll
;                 for (int ks = 0; ks < 4; ++ks) VNp[ks] = pack_step(VN[ks >> 1], ks & 1);
; #pragma unroll
;                 for (int mt = 0; mt < 2; ++mt) {
; #pragma unroll
;                     for (int g4 = 0; g4 < 4; ++g4) { const f32x4 ev = *(const LAS f32x4*)(sc_eg + 32 * mt + 8 * g4 + 4 * h);
; #pragma unroll
;                         for (int e = 0; e < 4; ++e) QS[mt][4 * g4 + e] *= ev[e]; }
; #pragma unroll
;                     for (int ks = 0; ks < 4; ++ks) if (ks < 2 * mt + 2) QS[mt] = MFMA32(frag_perm(Ab, 72, 32 * mt + r, ks, h), VNp[ks], QS[mt]);
;                 }
; #pragma unroll
;                 for (int mt = 0; mt < 2; ++mt)
; #pragma unroll
;                     for (int x = 0; x < 16; ++x) Vb[(32 * mt + crow(x, h)) * 128 + 32 * w + r] = f2bf(QS[mt][x]);
; #pragma unroll
;                 for (int mt = 0; mt < 2; ++mt)
; #pragma unroll
;                     for (int g4 = 0; g4 < 4; ++g4) { const f32x4 tv = *(const LAS f32x4*)(sc_tail + 32 * mt + 8 * g4 + 4 * h);
; #pragma unroll
;                         for (int e = 0; e < 4; ++e) VN[mt][4 * g4 + e] *= tv[e]; }
; #pragma unroll
;                 for (int ks = 0; ks < 4; ++ks) VNp[ks] = pack_step(VN[ks >> 1], ks & 1);
	v_lshlrev_b32_e32 v115, 16, v115
	s_waitcnt lgkmcnt(13)
	v_lshlrev_b32_e32 v116, 16, v116
	s_waitcnt lgkmcnt(12)
	v_lshlrev_b32_e32 v117, 16, v117
	s_waitcnt lgkmcnt(10)
	v_fma_f32 v114, -v82, v122, v114
	v_fma_f32 v115, -v83, v123, v115
	v_fma_f32 v116, -v84, v124, v116
	v_fma_f32 v117, -v85, v125, v117
	v_mul_f32_e32 v82, v118, v114
	v_mul_f32_e32 v83, v119, v115
	v_mul_f32_e32 v84, v120, v116
	v_mul_f32_e32 v85, v121, v117
	ds_read_u16 v114, v213 offset:47104
	ds_read_u16 v115, v213 offset:47360
	ds_read_u16 v116, v213 offset:47616
	ds_read_u16 v117, v213 offset:47872
	ds_read_b128 v[118:121], v214 offset:192
	ds_read_b128 v[122:125], v214 offset:704
	ds_read_b128 v[170:173], v212 offset:26144
	v_mfma_f32_32x32x16_bf16 v[98:113], v[142:145], v[230:233], v[98:113]
	v_lshlrev_b32_e32 v126, 16, v126
	s_waitcnt lgkmcnt(14)
	v_lshlrev_b32_e32 v127, 16, v127
	s_waitcnt lgkmcnt(13)
	v_lshlrev_b32_e32 v128, 16, v128
	s_waitcnt lgkmcnt(12)
	v_lshlrev_b32_e32 v129, 16, v129
	s_waitcnt lgkmcnt(10)
	v_fma_f32 v126, -v86, v134, v126
	v_fma_f32 v127, -v87, v135, v127
	v_fma_f32 v128, -v88, v136, v128
	v_fma_f32 v129, -v89, v137, v129
	v_mul_f32_e32 v86, v130, v126
	v_mul_f32_e32 v87, v131, v127
	v_mul_f32_e32 v88, v132, v128
	v_mul_f32_e32 v89, v133, v129
	ds_read_u16 v126, v213 offset:49152
	ds_read_u16 v127, v213 offset:49408
	ds_read_u16 v128, v213 offset:49664
	ds_read_u16 v129, v213 offset:49920
	ds_read_b128 v[130:133], v214 offset:224
	ds_read_b128 v[134:137], v214 offset:736
	ds_read_b128 v[142:145], v212 offset:26176
	v_mfma_f32_32x32x16_bf16 v[98:113], v[146:149], v[234:237], v[98:113]
	v_cvt_pk_bf16_f32 v146, v82, v83
	v_cvt_pk_bf16_f32 v148, v86, v87
	v_cvt_pk_bf16_f32 v147, v84, v85
	v_cvt_pk_bf16_f32 v149, v88, v89
	v_permlane32_swap_b32_e32 v146, v148
	s_nop 0
	v_permlane32_swap_b32_e32 v147, v149
	s_waitcnt lgkmcnt(13)
	v_lshlrev_b32_e32 v114, 16, v114
	s_waitcnt lgkmcnt(12)
	v_lshlrev_b32_e32 v115, 16, v115
	s_waitcnt lgkmcnt(11)
	v_lshlrev_b32_e32 v116, 16, v116
	s_waitcnt lgkmcnt(10)
	v_lshlrev_b32_e32 v117, 16, v117
	s_waitcnt lgkmcnt(8)
	v_fma_f32 v114, -v90, v122, v114
	v_fma_f32 v115, -v91, v123, v115
	v_fma_f32 v116, -v92, v124, v116
	v_fma_f32 v117, -v93, v125, v117
	v_mul_f32_e32 v90, v118, v114
	v_mul_f32_e32 v91, v119, v115
	v_mul_f32_e32 v92, v120, v116
	v_mul_f32_e32 v93, v121, v117
	v_mfma_f32_32x32x16_bf16 v[98:113], v[154:157], v[238:241], v[98:113]
	s_waitcnt lgkmcnt(6)
	v_lshlrev_b32_e32 v126, 16, v126
	s_waitcnt lgkmcnt(5)
	v_lshlrev_b32_e32 v127, 16, v127
	s_waitcnt lgkmcnt(4)
	v_lshlrev_b32_e32 v128, 16, v128
	s_waitcnt lgkmcnt(3)
	v_lshlrev_b32_e32 v129, 16, v129
	s_waitcnt lgkmcnt(1)
	v_fma_f32 v126, -v94, v134, v126
	v_fma_f32 v127, -v95, v135, v127
	v_fma_f32 v128, -v96, v136, v128
	v_fma_f32 v129, -v97, v137, v129
	v_mul_f32_e32 v94, v130, v126
	v_mul_f32_e32 v95, v131, v127
	v_mul_f32_e32 v96, v132, v128
	v_mul_f32_e32 v97, v133, v129
	ds_read_b128 v[154:157], v212 offset:26208
	v_mfma_f32_32x32x16_bf16 v[98:113], v[162:165], v[242:245], v[98:113]
	v_cvt_pk_bf16_f32 v162, v90, v91
	v_cvt_pk_bf16_f32 v164, v94, v95
	v_cvt_pk_bf16_f32 v163, v92, v93
	v_cvt_pk_bf16_f32 v165, v96, v97
	v_permlane32_swap_b32_e32 v162, v164
	s_nop 0
	v_permlane32_swap_b32_e32 v163, v165
	v_mfma_f32_32x32x16_bf16 v[98:113], v[166:169], v[246:249], v[98:113]
	ds_read_b32 v130, v217
	ds_read_b128 v[134:137], v214 offset:512
	ds_read_b128 v[166:169], v212 offset:26240
	v_mfma_f32_32x32x16_bf16 v[114:129], v[138:141], v[218:221], 0
	s_waitcnt lgkmcnt(2)
	v_mul_f32_e32 v50, v50, v130
	v_mul_f32_e32 v51, v51, v130
	v_mul_f32_e32 v52, v52, v130
	v_mul_f32_e32 v53, v53, v130
	v_mul_f32_e32 v54, v54, v130
	v_mul_f32_e32 v55, v55, v130
	v_mul_f32_e32 v56, v56, v130
	v_mul_f32_e32 v57, v57, v130
	ds_read_b128 v[138:141], v214 offset:544
	v_mfma_f32_32x32x16_bf16 v[114:129], v[170:173], v[222:225], v[114:129]
	v_mul_f32_e32 v58, v58, v130
	v_mul_f32_e32 v59, v59, v130
	v_mul_f32_e32 v60, v60, v130
	v_mul_f32_e32 v61, v61, v130
	v_mul_f32_e32 v62, v62, v130
	v_mul_f32_e32 v63, v63, v130
	v_mul_f32_e32 v64, v64, v130
	v_mul_f32_e32 v65, v65, v130
	v_mul_f32_e32 v34, v34, v130
	v_mul_f32_e32 v35, v35, v130
	s_waitcnt lgkmcnt(2)
	v_mul_f32_e32 v98, v98, v134
	v_mul_f32_e32 v99, v99, v135
	v_mul_f32_e32 v100, v100, v136
	v_mul_f32_e32 v101, v101, v137
	ds_read_b128 v[134:137], v214 offset:576
	ds_read_b128 v[170:173], v212 offset:26272
	v_mfma_f32_32x32x16_bf16 v[114:129], v[142:145], v[226:229], v[114:129]
	v_mul_f32_e32 v36, v36, v130
	v_mul_f32_e32 v37, v37, v130
	v_mul_f32_e32 v38, v38, v130
	v_mul_f32_e32 v39, v39, v130
	v_mul_f32_e32 v40, v40, v130
	v_mul_f32_e32 v41, v41, v130
	v_mul_f32_e32 v42, v42, v130
	v_mul_f32_e32 v43, v43, v130
	v_mul_f32_e32 v44, v44, v130
	v_mul_f32_e32 v45, v45, v130
	s_waitcnt lgkmcnt(2)
	v_mul_f32_e32 v102, v102, v138
	v_mul_f32_e32 v103, v103, v139
	v_mul_f32_e32 v104, v104, v140
	v_mul_f32_e32 v105, v105, v141
	ds_read_b128 v[138:141], v214 offset:608
	ds_read_b128 v[142:145], v212 offset:26304
	v_mfma_f32_32x32x16_bf16 v[114:129], v[154:157], v[230:233], v[114:129]
	v_mul_f32_e32 v46, v46, v130
	v_mul_f32_e32 v47, v47, v130
	v_mul_f32_e32 v48, v48, v130
	v_mul_f32_e32 v49, v49, v130
	v_mul_f32_e32 v18, v18, v130
	v_mul_f32_e32 v19, v19, v130
	v_mul_f32_e32 v20, v20, v130
	v_mul_f32_e32 v21, v21, v130
	v_mul_f32_e32 v22, v22, v130
	v_mul_f32_e32 v23, v23, v130
	s_waitcnt lgkmcnt(3)
; __device__ __forceinline__ int crow(int r, int hi) { return (r & 3) + 8 * (r >> 2) + 4 * hi; }
; #define LAS __attribute__((address_space(3)))
; __device__ __forceinline__ bf16_t f2bf(float f) { return (bf16_t)(cvtpk_s(f, 0.f) & 0xffffu); }
; __device__ __forceinline__ int crow(int x, int h) { return (x & 3) + 8 * (x >> 2) + 4 * h; }
; #define MFMA32(a, b, c) __builtin_amdgcn_mfma_f32_32x32x16_bf16((a), (b), (c), 0, 0, 0)
; template <int VAR> __device__ __forceinline__ void dn_scan3(LAS unsigned char* lds, const bf16_t* P, const float* AB, const bf16_t* TP, bf16_t* OB) {
;     ...
;                 for (int mt = 0; mt < 2; ++mt) {
; #pragma unroll
;                     for (int x = 0; x < 16; ++x) VN[mt][x] = 0.f;
; #pragma unroll
;                     for (int ks = 0; ks < 4; ++ks) if (ks < 2 * mt + 2) VN[mt] = MFMA32(frag_perm(Tb, 72, 32 * mt + r, ks, h), Xp[ks], VN[mt]);
;                 }
;                 bf16x8 VNp[4];
; #pragma unroll
;                 for (int ks = 0; ks < 4; ++ks) VNp[ks] = pack_step(VN[ks >> 1], ks & 1);
; #pragma unroll
;                 for (int mt = 0; mt < 2; ++mt) {
; #pragma unroll
;                     for (int g4 = 0; g4 < 4; ++g4) { const f32x4 ev = *(const LAS f32x4*)(sc_eg + 32 * mt + 8 * g4 + 4 * h);
; #pragma unroll
;                         for (int e = 0; e < 4; ++e) QS[mt][4 * g4 + e] *= ev[e]; }
; #pragma unroll
;                     for (int ks = 0; ks < 4; ++ks) if (ks < 2 * mt + 2) QS[mt] = MFMA32(frag_perm(Ab, 72, 32 * mt + r, ks, h), VNp[ks], QS[mt]);
;                 }
; #pragma unroll
;                 for (int mt = 0; mt < 2; ++mt)
; #pragma unroll
;                     for (int x = 0; x < 16; ++x) Vb[(32 * mt + crow(x, h)) * 128 + 32 * w + r] = f2bf(QS[mt][x]);
; #pragma unroll
;                 for (int mt = 0; mt < 2; ++mt)
; #pragma unroll
;                     for (int g4 = 0; g4 < 4; ++g4) { const f32x4 tv = *(const LAS f32x4*)(sc_tail + 32 * mt + 8 * g4 + 4 * h);
; #pragma unroll
;                         for (int e = 0; e < 4; ++e) VN[mt][4 * g4 + e] *= tv[e]; }
; #pragma unroll
;                 for (int ks = 0; ks < 4; ++ks) VNp[ks] = pack_step(VN[ks >> 1], ks & 1);
	v_mul_f32_e32 v106, v106, v134
	v_mul_f32_e32 v107, v107, v135
	v_mul_f32_e32 v108, v108, v136
	v_mul_f32_e32 v109, v109, v137
	ds_read_b128 v[154:157], v212 offset:26336
	v_mfma_f32_32x32x16_bf16 v[114:129], v[166:169], v[234:237], v[114:129]
	v_mul_f32_e32 v24, v24, v130
	v_mul_f32_e32 v25, v25, v130
	v_mul_f32_e32 v26, v26, v130
	v_mul_f32_e32 v27, v27, v130
	v_mul_f32_e32 v28, v28, v130
	v_mul_f32_e32 v29, v29, v130
	v_mul_f32_e32 v30, v30, v130
	v_mul_f32_e32 v31, v31, v130
	v_mul_f32_e32 v32, v32, v130
	v_mul_f32_e32 v33, v33, v130
	s_waitcnt lgkmcnt(2)
	v_mul_f32_e32 v110, v110, v138
	v_mul_f32_e32 v111, v111, v139
	v_mul_f32_e32 v112, v112, v140
	v_mul_f32_e32 v113, v113, v141
	ds_read_b128 v[134:137], v215 offset:51200
	ds_read_b128 v[138:141], v215 offset:51232
	v_mfma_f32_32x32x16_bf16 v[114:129], v[170:173], v[238:241], v[114:129]
	v_mul_f32_e32 v2, v2, v130
	v_mul_f32_e32 v3, v3, v130
	v_mul_f32_e32 v4, v4, v130
	v_mul_f32_e32 v5, v5, v130
	v_mul_f32_e32 v6, v6, v130
	v_mul_f32_e32 v7, v7, v130
	v_mul_f32_e32 v8, v8, v130
	v_mul_f32_e32 v9, v9, v130
	ds_read_b128 v[166:169], v215 offset:55808
	ds_read_b128 v[170:173], v215 offset:55840
	s_waitcnt lgkmcnt(5)
	v_mfma_f32_32x32x16_bf16 v[114:129], v[142:145], v[242:245], v[114:129]
	v_mul_f32_e32 v10, v10, v130
	v_mul_f32_e32 v11, v11, v130
	v_mul_f32_e32 v12, v12, v130
	v_mul_f32_e32 v13, v13, v130
	v_mul_f32_e32 v14, v14, v130
	v_mul_f32_e32 v15, v15, v130
	v_mul_f32_e32 v16, v16, v130
	v_mul_f32_e32 v17, v17, v130
	ds_read_b128 v[142:145], v215 offset:55872
	ds_read_b128 v[174:177], v215 offset:55904
	s_waitcnt lgkmcnt(6)
	v_mfma_f32_32x32x16_bf16 v[114:129], v[154:157], v[246:249], v[114:129]
	ds_read_b128 v[130:133], v214 offset:640
	ds_read_b128 v[154:157], v214 offset:672
	s_waitcnt lgkmcnt(7)
	v_mfma_f32_32x32x16_bf16 v[66:81], v[134:137], v[150:153], 0
	ds_read_b128 v[134:137], v214 offset:704
	ds_read_b128 v[218:221], v214 offset:736
	s_waitcnt lgkmcnt(8)
	v_mfma_f32_32x32x16_bf16 v[66:81], v[138:141], v[158:161], v[66:81]
	ds_read_b128 v[138:141], v214 offset:768
	ds_read_b128 v[222:225], v214 offset:800
	s_waitcnt lgkmcnt(9)
	v_mfma_f32_32x32x16_bf16 v[82:97], v[166:169], v[150:153], 0
	ds_read_b128 v[150:153], v214 offset:832
	ds_read_b128 v[166:169], v214 offset:864
	s_waitcnt lgkmcnt(10)
	v_mfma_f32_32x32x16_bf16 v[82:97], v[170:173], v[158:161], v[82:97]
	s_waitcnt lgkmcnt(7)
	v_mul_f32_e32 v114, v114, v130
	v_mul_f32_e32 v115, v115, v131
	v_mul_f32_e32 v116, v116, v132
	v_mul_f32_e32 v117, v117, v133
	s_waitcnt lgkmcnt(6)
	v_mul_f32_e32 v118, v118, v154
	v_mul_f32_e32 v119, v119, v155
	v_mul_f32_e32 v120, v120, v156
	v_mul_f32_e32 v121, v121, v157
	ds_read_b128 v[130:133], v215 offset:60416
	ds_read_b128 v[154:157], v215 offset:60448
	v_mfma_f32_32x32x16_bf16 v[82:97], v[142:145], v[146:149], v[82:97]
	s_waitcnt lgkmcnt(7)
	v_mul_f32_e32 v122, v122, v134
	v_mul_f32_e32 v123, v123, v135
	v_mul_f32_e32 v124, v124, v136
	v_mul_f32_e32 v125, v125, v137
	s_waitcnt lgkmcnt(6)
	v_mul_f32_e32 v126, v126, v218
	v_mul_f32_e32 v127, v127, v219
	v_mul_f32_e32 v128, v128, v220
	v_mul_f32_e32 v129, v129, v221
	v_mfma_f32_32x32x16_bf16 v[82:97], v[174:177], v[162:165], v[82:97]
	v_add_u32_e32 v134, s41, v211
	v_add_u32_e32 v135, s41, v201
	v_and_b32_e32 v136, 0xffff, v180
	v_lshrrev_b32_e32 v137, 16, v180
	v_add_u32_e32 v136, s41, v136
	v_add_u32_e32 v137, s41, v137
	ds_read_b64_tr_b16 v[158:159], v134 offset:0
	ds_read_b64_tr_b16 v[160:161], v135 offset:0
	ds_read_b64_tr_b16 v[162:163], v134 offset:64
	ds_read_b64_tr_b16 v[164:165], v135 offset:64
	v_cvt_pk_bf16_f32 v142, v66, v67
	v_cvt_pk_bf16_f32 v144, v70, v71
	v_cvt_pk_bf16_f32 v143, v68, v69
	v_cvt_pk_bf16_f32 v145, v72, v73
	v_cvt_pk_bf16_f32 v146, v74, v75
	v_cvt_pk_bf16_f32 v148, v78, v79
	v_cvt_pk_bf16_f32 v147, v76, v77
	v_cvt_pk_bf16_f32 v149, v80, v81
	v_permlane32_swap_b32_e32 v142, v144
	v_permlane32_swap_b32_e32 v143, v145
	v_permlane32_swap_b32_e32 v146, v148
	v_permlane32_swap_b32_e32 v147, v149
	s_waitcnt lgkmcnt(9)
	v_mul_f32_e32 v66, v66, v138
	v_mul_f32_e32 v67, v67, v139
	v_mul_f32_e32 v68, v68, v140
	v_mul_f32_e32 v69, v69, v141
	s_waitcnt lgkmcnt(8)
	v_mul_f32_e32 v70, v70, v222
	v_mul_f32_e32 v71, v71, v223
	v_mul_f32_e32 v72, v72, v224
	v_mul_f32_e32 v73, v73, v225
	s_waitcnt lgkmcnt(7)
	v_mul_f32_e32 v74, v74, v150
	v_mul_f32_e32 v75, v75, v151
	v_mul_f32_e32 v76, v76, v152
	v_mul_f32_e32 v77, v77, v153
	s_waitcnt lgkmcnt(6)
	v_mul_f32_e32 v78, v78, v166
	v_mul_f32_e32 v79, v79, v167
	v_mul_f32_e32 v80, v80, v168
	v_mul_f32_e32 v81, v81, v169
	v_cvt_pk_bf16_f32 v138, v66, v71
	v_cvt_pk_bf16_f32 v139, v76, v81
	v_cvt_pk_bf16_f32 v140, v67, v72
	v_cvt_pk_bf16_f32 v141, v77, v78
	v_cvt_pk_bf16_f32 v150, v68, v73
	v_cvt_pk_bf16_f32 v151, v74, v79
	v_cvt_pk_bf16_f32 v152, v69, v70
	v_cvt_pk_bf16_f32 v153, v75, v80
	ds_read_b64_tr_b16 v[166:167], v134 offset:128
	ds_read_b64_tr_b16 v[168:169], v135 offset:128
	ds_read_b64_tr_b16 v[170:171], v134 offset:192
	ds_read_b64_tr_b16 v[172:173], v135 offset:192
	ds_read_b64_tr_b16 v[174:175], v136 offset:0
	ds_read_b64_tr_b16 v[176:177], v137 offset:0
	ds_read_b64_tr_b16 v[218:219], v136 offset:64
	ds_read_b64_tr_b16 v[220:221], v137 offset:64
	s_waitcnt lgkmcnt(13)
	v_mfma_f32_32x32x16_bf16 v[98:113], v[130:133], v[142:145], v[98:113]
	ds_read_b128 v[130:133], v215 offset:65024
	ds_read_b128 v[222:225], v215 offset:65056
	s_waitcnt lgkmcnt(14)
; __device__ __forceinline__ int crow(int r, int hi) { return (r & 3) + 8 * (r >> 2) + 4 * hi; }
; #define LAS __attribute__((address_space(3)))
; __device__ __forceinline__ bf16_t f2bf(float f) { return (bf16_t)(cvtpk_s(f, 0.f) & 0xffffu); }
; __device__ __forceinline__ int crow(int x, int h) { return (x & 3) + 8 * (x >> 2) + 4 * h; }
; #define MFMA32(a, b, c) __builtin_amdgcn_mfma_f32_32x32x16_bf16((a), (b), (c), 0, 0, 0)
; template <int VAR> __device__ __forceinline__ void dn_scan3(LAS unsigned char* lds, const bf16_t* P, const float* AB, const bf16_t* TP, bf16_t* OB) {
;     ...
;                     for (int ks = 0; ks < 4; ++ks) if (ks < 2 * mt + 2) QS[mt] = MFMA32(frag_perm(Ab, 72, 32 * mt + r, ks, h), VNp[ks], QS[mt]);
;                 }
; #pragma unroll
;                 for (int mt = 0; mt < 2; ++mt)
; #pragma unroll
;                     for (int x = 0; x < 16; ++x) Vb[(32 * mt + crow(x, h)) * 128 + 32 * w + r] = f2bf(QS[mt][x]);
; #pragma unroll
;                 for (int mt = 0; mt < 2; ++mt)
; #pragma unroll
;                     for (int g4 = 0; g4 < 4; ++g4) { const f32x4 tv = *(const LAS f32x4*)(sc_tail + 32 * mt + 8 * g4 + 4 * h);
; #pragma unroll
;                         for (int e = 0; e < 4; ++e) VN[mt][4 * g4 + e] *= tv[e]; }
; #pragma unroll
;                 for (int ks = 0; ks < 4; ++ks) VNp[ks] = pack_step(VN[ks >> 1], ks & 1);
;                 const float dl = sc_dl[0];
; #pragma unroll
;                 for (int kt = 0; kt < 4; ++kt)
; #pragma unroll
;                     for (int x = 0; x < 16; ++x) S[kt][x] *= dl;
; #pragma unroll
;                 for (int ks = 0; ks < 4; ++ks) {
; #pragma unroll
;                     for (int kt = 0; kt < 4; ++kt) S[kt] = MFMA32(frag_tr(Kb, 136, 32 * kt, ks, lane), VNp[ks], S[kt]);
	v_mfma_f32_32x32x16_bf16 v[98:113], v[154:157], v[146:149], v[98:113]
	ds_read_b128 v[154:157], v214 offset:896
	ds_read_b128 v[226:229], v214 offset:928
	ds_read_b64_tr_b16 v[230:231], v136 offset:128
	ds_read_b64_tr_b16 v[232:233], v137 offset:128
	ds_read_b64_tr_b16 v[234:235], v136 offset:192
	ds_read_b64_tr_b16 v[236:237], v137 offset:192
	ds_read_b64_tr_b16 v[238:239], v134 offset:8704
	ds_read_b64_tr_b16 v[240:241], v135 offset:8704
	v_mfma_f32_32x32x16_bf16 v[50:65], v[158:161], v[138:141], v[50:65]
	ds_read_b128 v[158:161], v214 offset:960
	ds_read_b128 v[242:245], v214 offset:992
	v_mfma_f32_32x32x16_bf16 v[34:49], v[162:165], v[138:141], v[34:49]
	v_cvt_pk_bf16_f32 v162, v82, v83
	v_cvt_pk_bf16_f32 v164, v86, v87
	v_cvt_pk_bf16_f32 v163, v84, v85
	v_cvt_pk_bf16_f32 v165, v88, v89
	v_permlane32_swap_b32_e32 v162, v164
	s_nop 0
	v_permlane32_swap_b32_e32 v163, v165
	v_mfma_f32_32x32x16_bf16 v[18:33], v[166:169], v[138:141], v[18:33]
	v_cvt_pk_bf16_f32 v166, v90, v91
	v_cvt_pk_bf16_f32 v168, v94, v95
	v_cvt_pk_bf16_f32 v167, v92, v93
	v_cvt_pk_bf16_f32 v169, v96, v97
	v_permlane32_swap_b32_e32 v166, v168
	s_nop 0
	v_permlane32_swap_b32_e32 v167, v169
	v_mfma_f32_32x32x16_bf16 v[2:17], v[170:173], v[138:141], v[2:17]
	s_waitcnt lgkmcnt(9)
	v_mul_f32_e32 v82, v82, v154
	v_mul_f32_e32 v83, v83, v155
	v_mul_f32_e32 v84, v84, v156
	v_mul_f32_e32 v85, v85, v157
	s_waitcnt lgkmcnt(8)
	v_mul_f32_e32 v86, v86, v226
	v_mul_f32_e32 v87, v87, v227
	v_mul_f32_e32 v88, v88, v228
	v_mul_f32_e32 v89, v89, v229
	ds_read_b128 v[154:157], v215 offset:65088
	ds_read_b128 v[170:173], v215 offset:65120
	v_mfma_f32_32x32x16_bf16 v[50:65], v[174:177], v[150:153], v[50:65]
	v_cvt_pk_bf16_f32 v174, v98, s0
	ds_write_b16 v213, v174 offset:34816
	v_cvt_pk_bf16_f32 v175, v99, s0
	ds_write_b16 v213, v175 offset:35072
	s_waitcnt lgkmcnt(5)
	v_mul_f32_e32 v90, v90, v158
	v_mul_f32_e32 v91, v91, v159
	v_mul_f32_e32 v92, v92, v160
	v_mul_f32_e32 v93, v93, v161
	s_waitcnt lgkmcnt(4)
	v_mul_f32_e32 v94, v94, v242
	v_mul_f32_e32 v95, v95, v243
	v_mul_f32_e32 v96, v96, v244
	v_mul_f32_e32 v97, v97, v245
	ds_read_b64_tr_b16 v[158:159], v134 offset:8768
	ds_read_b64_tr_b16 v[160:161], v135 offset:8768
	v_mfma_f32_32x32x16_bf16 v[34:49], v[218:221], v[150:153], v[34:49]
	v_cvt_pk_bf16_f32 v176, v100, s0
	ds_write_b16 v213, v176 offset:35328
	v_cvt_pk_bf16_f32 v177, v101, s0
	ds_write_b16 v213, v177 offset:35584
	v_cvt_pk_bf16_f32 v218, v82, v87
	v_cvt_pk_bf16_f32 v219, v92, v97
	v_cvt_pk_bf16_f32 v220, v83, v88
	v_cvt_pk_bf16_f32 v221, v93, v94
	ds_read_b64_tr_b16 v[226:227], v134 offset:8832
	ds_read_b64_tr_b16 v[228:229], v135 offset:8832
	v_mfma_f32_32x32x16_bf16 v[18:33], v[230:233], v[150:153], v[18:33]
	v_cvt_pk_bf16_f32 v174, v102, s0
	ds_write_b16 v213, v174 offset:36864
	v_cvt_pk_bf16_f32 v175, v103, s0
	ds_write_b16 v213, v175 offset:37120
	v_cvt_pk_bf16_f32 v230, v84, v89
	v_cvt_pk_bf16_f32 v231, v90, v95
	v_cvt_pk_bf16_f32 v232, v85, v86
	v_cvt_pk_bf16_f32 v233, v91, v96
	v_mfma_f32_32x32x16_bf16 v[2:17], v[234:237], v[150:153], v[2:17]
	v_cvt_pk_bf16_f32 v176, v104, s0
	ds_write_b16 v213, v176 offset:37376
	v_cvt_pk_bf16_f32 v177, v105, s0
	ds_write_b16 v213, v177 offset:37632
	v_mfma_f32_32x32x16_bf16 v[114:129], v[130:133], v[142:145], v[114:129]
	v_cvt_pk_bf16_f32 v174, v106, s0
	ds_write_b16 v213, v174 offset:38912
	v_cvt_pk_bf16_f32 v175, v107, s0
	ds_write_b16 v213, v175 offset:39168
	ds_read_b64_tr_b16 v[130:131], v134 offset:8896
	ds_read_b64_tr_b16 v[132:133], v135 offset:8896
	ds_read_b64_tr_b16 v[138:139], v136 offset:8704
	ds_read_b64_tr_b16 v[140:141], v137 offset:8704
	v_mfma_f32_32x32x16_bf16 v[114:129], v[222:225], v[146:149], v[114:129]
	v_cvt_pk_bf16_f32 v176, v108, s0
	ds_write_b16 v213, v176 offset:39424
	v_cvt_pk_bf16_f32 v177, v109, s0
	ds_write_b16 v213, v177 offset:39680
	ds_read_b64_tr_b16 v[142:143], v136 offset:8768
	ds_read_b64_tr_b16 v[144:145], v137 offset:8768
	ds_read_b64_tr_b16 v[146:147], v136 offset:8832
	ds_read_b64_tr_b16 v[148:149], v137 offset:8832
	v_mfma_f32_32x32x16_bf16 v[114:129], v[154:157], v[162:165], v[114:129]
	v_cvt_pk_bf16_f32 v174, v110, s0
	ds_write_b16 v213, v174 offset:40960
	v_cvt_pk_bf16_f32 v175, v111, s0
	ds_write_b16 v213, v175 offset:41216
	ds_read_b64_tr_b16 v[150:151], v136 offset:8896
	ds_read_b64_tr_b16 v[152:153], v137 offset:8896
	v_mfma_f32_32x32x16_bf16 v[114:129], v[170:173], v[166:169], v[114:129]
	v_cvt_pk_bf16_f32 v176, v112, s0
	ds_write_b16 v213, v176 offset:41472
	v_cvt_pk_bf16_f32 v177, v113, s0
	ds_write_b16 v213, v177 offset:41728
	ds_read_b32 v154, v179 offset:34816
	ds_read_b32 v155, v179 offset:35840
	ds_read_b32 v156, v179 offset:36864
	ds_read_b32 v157, v179 offset:37888
	ds_read_b32 v162, v179 offset:38912
	ds_read_b32 v163, v179 offset:39936
	ds_read_b32 v164, v179 offset:40960
	ds_read_b32 v165, v179 offset:41984
	v_mfma_f32_32x32x16_bf16 v[50:65], v[238:241], v[218:221], v[50:65]
	v_cvt_pk_bf16_f32 v174, v114, s0
	ds_write_b16 v213, v174 offset:43008
	v_cvt_pk_bf16_f32 v175, v115, s0
	ds_write_b16 v213, v175 offset:43264
	v_cvt_pk_bf16_f32 v176, v116, s0
	ds_write_b16 v213, v176 offset:43520
	v_cvt_pk_bf16_f32 v177, v117, s0
	ds_write_b16 v213, v177 offset:43776
	v_add_u32_e32 v195, s60, v194
	s_waitcnt lgkmcnt(11)
; #define BAR_LDS() do { asm volatile("s_waitcnt lgkmcnt(0)" ::: "memory"); __builtin_amdgcn_s_barrier(); asm volatile("" ::: "memory"); } while (0)
; #define MFMA32(a, b, c) __builtin_amdgcn_mfma_f32_32x32x16_bf16((a), (b), (c), 0, 0, 0)
; template <int VAR> __device__ __forceinline__ void dn_scan3(LAS unsigned char* lds, const bf16_t* P, const float* AB, const bf16_t* TP, bf16_t* OB) {
;     ...
;                 for (int ks = 0; ks < 8; ++ks) {
;                     const bf16x8 sp = pack_step(S[ks >> 1], ks & 1);
;     ...
;                 for (int ks = 0; ks < 4; ++ks) {
; #pragma unroll
;                     for (int kt = 0; kt < 4; ++kt) S[kt] = MFMA32(frag_tr(Kb, 136, 32 * kt, ks, lane), VNp[ks], S[kt]);
;                 }
;                 }
;                 BAR_LDS();
;             }
	global_atomic_pk_add_bf16 v195, v154, s[42:43]
	v_add_u32_e32 v200, s61, v194
	s_waitcnt lgkmcnt(10)
	global_atomic_pk_add_bf16 v200, v155, s[42:43]
	v_mfma_f32_32x32x16_bf16 v[34:49], v[158:161], v[218:221], v[34:49]
	v_cvt_pk_bf16_f32 v174, v118, s0
	ds_write_b16 v213, v174 offset:45056
	v_cvt_pk_bf16_f32 v175, v119, s0
	ds_write_b16 v213, v175 offset:45312
	v_cvt_pk_bf16_f32 v176, v120, s0
	ds_write_b16 v213, v176 offset:45568
	v_cvt_pk_bf16_f32 v177, v121, s0
	ds_write_b16 v213, v177 offset:45824
	v_add_u32_e32 v195, s62, v195
	s_waitcnt lgkmcnt(13)
	global_atomic_pk_add_bf16 v195, v156, s[42:43]
	v_add_u32_e32 v200, s62, v200
	s_waitcnt lgkmcnt(12)
	global_atomic_pk_add_bf16 v200, v157, s[42:43]
	v_mfma_f32_32x32x16_bf16 v[18:33], v[226:229], v[218:221], v[18:33]
	v_cvt_pk_bf16_f32 v174, v122, s0
	ds_write_b16 v213, v174 offset:47104
	v_cvt_pk_bf16_f32 v175, v123, s0
	ds_write_b16 v213, v175 offset:47360
	v_cvt_pk_bf16_f32 v176, v124, s0
	ds_write_b16 v213, v176 offset:47616
	v_cvt_pk_bf16_f32 v177, v125, s0
	ds_write_b16 v213, v177 offset:47872
	v_add_u32_e32 v195, s62, v195
	global_atomic_pk_add_bf16 v195, v162, s[42:43]
	v_add_u32_e32 v200, s62, v200
	s_waitcnt lgkmcnt(14)
	global_atomic_pk_add_bf16 v200, v163, s[42:43]
	v_mfma_f32_32x32x16_bf16 v[2:17], v[130:133], v[218:221], v[2:17]
	v_cvt_pk_bf16_f32 v174, v126, s0
	ds_write_b16 v213, v174 offset:49152
	v_cvt_pk_bf16_f32 v175, v127, s0
	ds_write_b16 v213, v175 offset:49408
	v_cvt_pk_bf16_f32 v176, v128, s0
	ds_write_b16 v213, v176 offset:49664
	v_cvt_pk_bf16_f32 v177, v129, s0
	ds_write_b16 v213, v177 offset:49920
	v_add_u32_e32 v195, s62, v195
	global_atomic_pk_add_bf16 v195, v164, s[42:43]
	v_add_u32_e32 v200, s62, v200
	global_atomic_pk_add_bf16 v200, v165, s[42:43]
	v_mfma_f32_32x32x16_bf16 v[50:65], v[138:141], v[230:233], v[50:65]
	ds_read_b32 v130, v179 offset:43008
	ds_read_b32 v131, v179 offset:44032
	ds_read_b32 v132, v179 offset:45056
	ds_read_b32 v133, v179 offset:46080
	ds_read_b32 v138, v179 offset:47104
	ds_read_b32 v139, v179 offset:48128
	ds_read_b32 v140, v179 offset:49152
	ds_read_b32 v141, v179 offset:50176
	v_mfma_f32_32x32x16_bf16 v[34:49], v[142:145], v[230:233], v[34:49]
	v_add_u32_e32 v195, s62, v195
	s_waitcnt lgkmcnt(7)
	global_atomic_pk_add_bf16 v195, v130, s[42:43]
	v_add_u32_e32 v200, s62, v200
	s_waitcnt lgkmcnt(6)
	global_atomic_pk_add_bf16 v200, v131, s[42:43]
	v_mfma_f32_32x32x16_bf16 v[18:33], v[146:149], v[230:233], v[18:33]
	v_add_u32_e32 v195, s62, v195
	s_waitcnt lgkmcnt(5)
	global_atomic_pk_add_bf16 v195, v132, s[42:43]
	v_add_u32_e32 v200, s62, v200
	s_waitcnt lgkmcnt(4)
	global_atomic_pk_add_bf16 v200, v133, s[42:43]
	v_mfma_f32_32x32x16_bf16 v[2:17], v[150:153], v[230:233], v[2:17]
	v_add_u32_e32 v195, s62, v195
	s_waitcnt lgkmcnt(3)
	global_atomic_pk_add_bf16 v195, v138, s[42:43]
	v_add_u32_e32 v200, s62, v200
	s_waitcnt lgkmcnt(2)
	global_atomic_pk_add_bf16 v200, v139, s[42:43]
	v_cvt_pk_bf16_f32 v218, v50, v51
	v_cvt_pk_bf16_f32 v220, v54, v55
	v_cvt_pk_bf16_f32 v219, v52, v53
	v_cvt_pk_bf16_f32 v221, v56, v57
	v_cvt_pk_bf16_f32 v222, v58, v59
	v_cvt_pk_bf16_f32 v224, v62, v63
	v_cvt_pk_bf16_f32 v223, v60, v61
	v_cvt_pk_bf16_f32 v225, v64, v65
	v_permlane32_swap_b32_e32 v218, v220
	v_permlane32_swap_b32_e32 v219, v221
	v_permlane32_swap_b32_e32 v222, v224
	v_permlane32_swap_b32_e32 v223, v225
	v_add_u32_e32 v195, s62, v195
	s_waitcnt lgkmcnt(1)
	global_atomic_pk_add_bf16 v195, v140, s[42:43]
	v_add_u32_e32 v200, s62, v200
	s_waitcnt lgkmcnt(0)
	global_atomic_pk_add_bf16 v200, v141, s[42:43]
	s_waitcnt lgkmcnt(0)
	s_barrier
	s_add_i32 s40, s40, 1
	s_cmpk_lg_i32 s40, 0x104
	s_cbranch_scc1 .LBB0_377
	s_setprio 0
